# UP epilogue: counted wait for the conv weight loads instead of draining the wave's halo stores
# baseline (speedup 1.0000x reference)
.Lup_pv0_skip:
	v_add_u32_e32 v210, v210, v229
	s_andn2_b64 vcc, exec, s[10:11]
	s_cbranch_vccnz .Lup_w0
	s_and_b32 s1, s54, 7
	s_cmp_lg_u32 s1, 7
	s_cbranch_scc1 .Lup_w2
	s_waitcnt vmcnt(4) lgkmcnt(0)
	s_branch .Lup_wd
.Lup_w2:
	s_waitcnt vmcnt(2) lgkmcnt(0)
	s_branch .Lup_wd
.Lup_w0:
	s_waitcnt vmcnt(0) lgkmcnt(0)
.Lup_wd:
	v_cndmask_b32_e64 v170, v150, v166, s[38:39]
	v_cndmask_b32_e64 v171, v151, v167, s[38:39]
	v_cndmask_b32_e64 v172, v152, v168, s[38:39]
	v_cndmask_b32_e64 v173, v153, v169, s[38:39]
	v_cndmask_b32_e64 v174, v146, v162, s[38:39]
	v_cndmask_b32_e64 v175, v147, v163, s[38:39]
	v_cndmask_b32_e64 v176, v148, v164, s[38:39]
	v_cndmask_b32_e64 v177, v149, v165, s[38:39]
	v_cndmask_b32_e64 v166, v150, v166, s[40:41]
	v_cndmask_b32_e64 v167, v151, v167, s[40:41]
	v_cndmask_b32_e64 v168, v152, v168, s[40:41]
	v_cndmask_b32_e64 v169, v153, v169, s[40:41]
	v_cndmask_b32_e64 v162, v146, v162, s[40:41]
	v_cndmask_b32_e64 v163, v147, v163, s[40:41]
	v_cndmask_b32_e64 v164, v148, v164, s[40:41]
	v_cndmask_b32_e64 v165, v149, v165, s[40:41]
	v_pk_fma_f32 v[178:179], v[126:127], v[150:151], v[130:131]
	v_pk_fma_f32 v[180:181], v[128:129], v[152:153], v[132:133]
	v_pk_fma_f32 v[182:183], v[118:119], v[146:147], v[110:111]
	v_pk_fma_f32 v[184:185], v[120:121], v[148:149], v[112:113]
	v_fmac_f32_dpp v178, v166, v134 row_ror:1 row_mask:0xf bank_mask:0xf
	v_fmac_f32_dpp v179, v167, v135 row_ror:1 row_mask:0xf bank_mask:0xf
	v_fmac_f32_dpp v180, v168, v136 row_ror:1 row_mask:0xf bank_mask:0xf
	v_fmac_f32_dpp v181, v169, v137 row_ror:1 row_mask:0xf bank_mask:0xf
	v_fmac_f32_dpp v182, v162, v114 row_ror:1 row_mask:0xf bank_mask:0xf
	v_fmac_f32_dpp v183, v163, v115 row_ror:1 row_mask:0xf bank_mask:0xf
	v_fmac_f32_dpp v184, v164, v116 row_ror:1 row_mask:0xf bank_mask:0xf
	v_fmac_f32_dpp v185, v165, v117 row_ror:1 row_mask:0xf bank_mask:0xf
	v_fmac_f32_dpp v178, v170, v122 row_ror:2 row_mask:0xf bank_mask:0xf
	v_fmac_f32_dpp v179, v171, v123 row_ror:2 row_mask:0xf bank_mask:0xf
	v_fmac_f32_dpp v180, v172, v124 row_ror:2 row_mask:0xf bank_mask:0xf
	v_fmac_f32_dpp v181, v173, v125 row_ror:2 row_mask:0xf bank_mask:0xf
	v_fmac_f32_dpp v182, v174, v106 row_ror:2 row_mask:0xf bank_mask:0xf
	v_fmac_f32_dpp v183, v175, v107 row_ror:2 row_mask:0xf bank_mask:0xf
	v_fmac_f32_dpp v184, v176, v108 row_ror:2 row_mask:0xf bank_mask:0xf
	v_fmac_f32_dpp v185, v177, v109 row_ror:2 row_mask:0xf bank_mask:0xf
	v_pk_mul_f32 v[166:167], v[178:179], v[188:189]
	v_pk_mul_f32 v[168:169], v[180:181], v[188:189]
	v_pk_mul_f32 v[162:163], v[182:183], v[188:189]
	v_pk_mul_f32 v[164:165], v[184:185], v[188:189]
	v_exp_f32_e32 v166, v166
	v_exp_f32_e32 v167, v167
	v_exp_f32_e32 v168, v168
	v_exp_f32_e32 v169, v169
	v_exp_f32_e32 v162, v162
	v_exp_f32_e32 v163, v163
	v_exp_f32_e32 v164, v164
	v_exp_f32_e32 v165, v165
	v_pk_add_f32 v[166:167], v[166:167], v[212:213]
	v_pk_add_f32 v[168:169], v[168:169], v[212:213]
	v_pk_add_f32 v[162:163], v[162:163], v[212:213]
	v_pk_add_f32 v[164:165], v[164:165], v[212:213]
	v_rcp_f32_e32 v166, v166
	v_rcp_f32_e32 v167, v167
	v_rcp_f32_e32 v168, v168
	v_rcp_f32_e32 v169, v169
	v_rcp_f32_e32 v162, v162
	v_rcp_f32_e32 v163, v163
	v_rcp_f32_e32 v164, v164
	v_rcp_f32_e32 v165, v165
	v_pk_mul_f32 v[170:171], v[178:179], v[166:167]
	v_pk_mul_f32 v[172:173], v[180:181], v[168:169]
	v_pk_mul_f32 v[174:175], v[182:183], v[162:163]
	v_pk_mul_f32 v[176:177], v[184:185], v[164:165]
	v_pk_mul_f32 v[170:171], v[158:159], v[170:171]
	v_pk_mul_f32 v[172:173], v[160:161], v[172:173]
	v_pk_mul_f32 v[174:175], v[154:155], v[174:175]
	v_pk_mul_f32 v[176:177], v[156:157], v[176:177]
	v_cvt_pk_bf16_f32 v178, v170, v171
	v_cvt_pk_bf16_f32 v179, v172, v173
	v_cvt_pk_bf16_f32 v180, v174, v175
	v_cvt_pk_bf16_f32 v181, v176, v177
	s_andn2_b64 exec, exec, s[20:21]
	global_store_dwordx4 v211, v[178:181], s[100:101]
	s_mov_b64 exec, s[20:21]
	s_cbranch_execz .Lup_nodefer
	v_lshl_add_u32 v162, v227, 3, s64
	v_add_u32_e32 v162, s24, v162
	v_add_u32_e32 v163, s63, v226
	v_lshl_add_u32 v163, s54, 1, v163
	v_mul_u32_u24_e32 v163, 0x2a00, v163
	v_lshl_add_u32 v162, v162, 2, v163
	s_add_u32 s4, s6, 0x1d460000
	s_addc_u32 s5, s7, 0
	global_store_dwordx4 v162, v[150:153], s[4:5]
	global_store_dwordx4 v162, v[146:149], s[4:5] offset:16
	s_add_u32 s4, s6, 0x1d660000
	s_addc_u32 s5, s7, 0
	global_store_dwordx4 v162, v[158:161], s[4:5]
	global_store_dwordx4 v162, v[154:157], s[4:5] offset:16
